# GEMM-3 replaced by the hand-written streaming GEMM (4 n-chunks per tile without pipeline drain)
# speedup vs baseline: 1.0103x; 1.0087x over previous
.LBB0_345:
	v_and_b32_e32 v246, 63, v208
	v_lshrrev_b32_e32 v247, 6, v208
	v_lshrrev_b32_e32 v248, 3, v246
	v_and_b32_e32 v249, 7, v246
	v_xor_b32_e32 v249, v249, v248
	v_lshlrev_b32_e32 v249, 4, v249
	v_lshl_add_u32 v250, v247, 5, v248
	v_lshl_add_u32 v234, v250, 11, v249
	v_add_u32_e32 v235, 0x4000, v234
	v_add_u32_e32 v236, 0x8000, v234
	v_add_u32_e32 v237, 0xc000, v234
	v_lshlrev_b32_e32 v238, 4, v246
	v_add_u32_e32 v239, 0x8000, v238
	v_add_u32_e32 v240, 0x10000, v238
	v_add_u32_e32 v241, 0x18000, v238
	v_readfirstlane_b32 s2, v247
	s_lshl_b32 s20, s2, 12
	v_and_b32_e32 v251, 15, v246
	v_lshrrev_b32_e32 v252, 4, v246
	v_and_b32_e32 v253, 7, v251
	v_xor_b32_e32 v253, v253, v252
	v_lshlrev_b32_e32 v253, 4, v253
	v_lshl_add_u32 v242, v251, 7, v253
	v_xor_b32_e32 v243, 64, v242
	s_mov_b32 s11, 0
	v_and_b32_e32 v244, 15, v208
	v_lshlrev_b32_e32 v244, 2, v244
	s_lshl_b32 s2, s10, 9
	s_add_i32 s2, s2, 0x36c80000
	v_add_u32_e32 v244, s2, v244
	v_mov_b32_e32 v245, s93
	v_add_co_u32_e32 v244, vcc, s92, v244
	s_nop 1
	v_addc_co_u32_e32 v245, vcc, 0, v245, vcc
	global_load_dword v246, v[244:245], off
	global_load_dword v247, v[244:245], off offset:64
	global_load_dword v248, v[244:245], off offset:128
	global_load_dword v249, v[244:245], off offset:192
	global_load_dword v250, v[244:245], off offset:256
	global_load_dword v251, v[244:245], off offset:320
	global_load_dword v252, v[244:245], off offset:384
	global_load_dword v253, v[244:245], off offset:448
	s_lshl_b32 s2, s10, 18
	s_add_i32 s2, s2, 0x1e000000
	s_add_u32 s12, s92, s2
	s_addc_u32 s13, s93, 0
	s_lshl_b32 s2, s11, 19
	s_lshl_b32 s21, s20, 5
	s_add_i32 s2, s2, s21
	s_add_i32 s2, s2, 0x34800000
	s_add_u32 s14, s92, s2
	s_addc_u32 s15, s93, 0
	s_mov_b32 s19, 0
	s_mov_b32 s17, 0
	s_add_i32 m0, s17, s20
	s_nop 0
	global_load_lds_dwordx4 v234, s[12:13]
	s_add_i32 m0, m0, 0x400
	s_nop 0
	global_load_lds_dwordx4 v235, s[12:13]
	s_add_i32 m0, m0, 0x400
	s_nop 0
	global_load_lds_dwordx4 v236, s[12:13]
	s_add_i32 m0, m0, 0x400
	s_nop 0
	global_load_lds_dwordx4 v237, s[12:13]
	s_add_u32 s12, s12, 128
	s_addc_u32 s13, s13, 0
	global_load_dwordx4 v[128:131], v238, s[14:15]
	global_load_dwordx4 v[132:135], v239, s[14:15]
	global_load_dwordx4 v[136:139], v240, s[14:15]
	global_load_dwordx4 v[140:143], v241, s[14:15]
	s_add_u32 s14, s14, 1024
	s_addc_u32 s15, s15, 0
	s_add_i32 s19, s19, 1
	global_load_dwordx4 v[144:147], v238, s[14:15]
	global_load_dwordx4 v[148:151], v239, s[14:15]
	global_load_dwordx4 v[152:155], v240, s[14:15]
	global_load_dwordx4 v[156:159], v241, s[14:15]
	s_add_u32 s14, s14, 1024
	s_addc_u32 s15, s15, 0
	s_add_i32 s19, s19, 1
	s_movk_i32 s17, 0x4000
	s_add_i32 m0, s17, s20
	s_nop 0
	global_load_lds_dwordx4 v234, s[12:13]
	s_add_i32 m0, m0, 0x400
	s_nop 0
	global_load_lds_dwordx4 v235, s[12:13]
	s_add_i32 m0, m0, 0x400
	s_nop 0
	global_load_lds_dwordx4 v236, s[12:13]
	s_add_i32 m0, m0, 0x400
	s_nop 0
	global_load_lds_dwordx4 v237, s[12:13]
	s_add_u32 s12, s12, 128
	s_addc_u32 s13, s13, 0
	global_load_dwordx4 v[160:163], v238, s[14:15]
	global_load_dwordx4 v[164:167], v239, s[14:15]
	global_load_dwordx4 v[168:171], v240, s[14:15]
	global_load_dwordx4 v[172:175], v241, s[14:15]
	s_add_u32 s14, s14, 1024
	s_addc_u32 s15, s15, 0
	s_add_i32 s19, s19, 1
	s_mov_b32 s16, 0
	s_mov_b32 s17, 0x8000
.Lg3_chunk:
	v_mov_b32_e32 v0, 0
	v_mov_b32_e32 v1, 0
	v_mov_b32_e32 v2, 0
	v_mov_b32_e32 v3, 0
	v_mov_b32_e32 v4, 0
	v_mov_b32_e32 v5, 0
	v_mov_b32_e32 v6, 0
	v_mov_b32_e32 v7, 0
	v_mov_b32_e32 v8, 0
	v_mov_b32_e32 v9, 0
	v_mov_b32_e32 v10, 0
	v_mov_b32_e32 v11, 0
	v_mov_b32_e32 v12, 0
	v_mov_b32_e32 v13, 0
	v_mov_b32_e32 v14, 0
	v_mov_b32_e32 v15, 0
	v_mov_b32_e32 v16, 0
	v_mov_b32_e32 v17, 0
	v_mov_b32_e32 v18, 0
	v_mov_b32_e32 v19, 0
	v_mov_b32_e32 v20, 0
	v_mov_b32_e32 v21, 0
	v_mov_b32_e32 v22, 0
	v_mov_b32_e32 v23, 0
	v_mov_b32_e32 v24, 0
	v_mov_b32_e32 v25, 0
	v_mov_b32_e32 v26, 0
	v_mov_b32_e32 v27, 0
	v_mov_b32_e32 v28, 0
	v_mov_b32_e32 v29, 0
	v_mov_b32_e32 v30, 0
	v_mov_b32_e32 v31, 0
	v_mov_b32_e32 v32, 0
	v_mov_b32_e32 v33, 0
	v_mov_b32_e32 v34, 0
	v_mov_b32_e32 v35, 0
	v_mov_b32_e32 v36, 0
	v_mov_b32_e32 v37, 0
	v_mov_b32_e32 v38, 0
	v_mov_b32_e32 v39, 0
	v_mov_b32_e32 v40, 0
	v_mov_b32_e32 v41, 0
	v_mov_b32_e32 v42, 0
	v_mov_b32_e32 v43, 0
	v_mov_b32_e32 v44, 0
	v_mov_b32_e32 v45, 0
	v_mov_b32_e32 v46, 0
	v_mov_b32_e32 v47, 0
	v_mov_b32_e32 v48, 0
	v_mov_b32_e32 v49, 0
	v_mov_b32_e32 v50, 0
	v_mov_b32_e32 v51, 0
	v_mov_b32_e32 v52, 0
	v_mov_b32_e32 v53, 0
	v_mov_b32_e32 v54, 0
	v_mov_b32_e32 v55, 0
	v_mov_b32_e32 v56, 0
	v_mov_b32_e32 v57, 0
	v_mov_b32_e32 v58, 0
	v_mov_b32_e32 v59, 0
	v_mov_b32_e32 v60, 0
	v_mov_b32_e32 v61, 0
	v_mov_b32_e32 v62, 0
	v_mov_b32_e32 v63, 0
	v_mov_b32_e32 v64, 0
	v_mov_b32_e32 v65, 0
	v_mov_b32_e32 v66, 0
	v_mov_b32_e32 v67, 0
	v_mov_b32_e32 v68, 0
	v_mov_b32_e32 v69, 0
	v_mov_b32_e32 v70, 0
	v_mov_b32_e32 v71, 0
	v_mov_b32_e32 v72, 0
	v_mov_b32_e32 v73, 0
	v_mov_b32_e32 v74, 0
	v_mov_b32_e32 v75, 0
	v_mov_b32_e32 v76, 0
	v_mov_b32_e32 v77, 0
	v_mov_b32_e32 v78, 0
	v_mov_b32_e32 v79, 0
	v_mov_b32_e32 v80, 0
	v_mov_b32_e32 v81, 0
	v_mov_b32_e32 v82, 0
	v_mov_b32_e32 v83, 0
	v_mov_b32_e32 v84, 0
	v_mov_b32_e32 v85, 0
	v_mov_b32_e32 v86, 0
	v_mov_b32_e32 v87, 0
	v_mov_b32_e32 v88, 0
	v_mov_b32_e32 v89, 0
	v_mov_b32_e32 v90, 0
	v_mov_b32_e32 v91, 0
	v_mov_b32_e32 v92, 0
	v_mov_b32_e32 v93, 0
	v_mov_b32_e32 v94, 0
	v_mov_b32_e32 v95, 0
	v_mov_b32_e32 v96, 0
	v_mov_b32_e32 v97, 0
	v_mov_b32_e32 v98, 0
	v_mov_b32_e32 v99, 0
	v_mov_b32_e32 v100, 0
	v_mov_b32_e32 v101, 0
	v_mov_b32_e32 v102, 0
	v_mov_b32_e32 v103, 0
	v_mov_b32_e32 v104, 0
	v_mov_b32_e32 v105, 0
	v_mov_b32_e32 v106, 0
	v_mov_b32_e32 v107, 0
	v_mov_b32_e32 v108, 0
	v_mov_b32_e32 v109, 0
	v_mov_b32_e32 v110, 0
	v_mov_b32_e32 v111, 0
	v_mov_b32_e32 v112, 0
	v_mov_b32_e32 v113, 0
	v_mov_b32_e32 v114, 0
	v_mov_b32_e32 v115, 0
	v_mov_b32_e32 v116, 0
	v_mov_b32_e32 v117, 0
	v_mov_b32_e32 v118, 0
	v_mov_b32_e32 v119, 0
	v_mov_b32_e32 v120, 0
	v_mov_b32_e32 v121, 0
	v_mov_b32_e32 v122, 0
	v_mov_b32_e32 v123, 0
	v_mov_b32_e32 v124, 0
	v_mov_b32_e32 v125, 0
	v_mov_b32_e32 v126, 0
	v_mov_b32_e32 v127, 0
	s_mov_b32 s19, 3
	s_mov_b32 s18, 0
.Lg3_loop:
	s_waitcnt vmcnt(12)
	s_barrier
	global_load_dwordx4 v[176:179], v238, s[14:15]
	global_load_dwordx4 v[182:185], v239, s[14:15]
	global_load_dwordx4 v[186:189], v240, s[14:15]
	global_load_dwordx4 v[194:197], v241, s[14:15]
	s_cmp_eq_u32 s19, 31
	s_cbranch_scc1 .Lg3_sww0
	s_add_u32 s14, s14, 1024
	s_addc_u32 s15, s15, 0
	s_branch .Lg3_swdw0
.Lg3_sww0:
	s_cmp_lt_u32 s11, 3
	s_cbranch_scc1 .Lg3_wsamew0
	s_add_i32 s21, s10, s95
	s_cmpk_gt_i32 s21, 0x1ff
	s_cbranch_scc1 .Lg3_wndw0
	s_mov_b32 s21, 0
	s_lshl_b32 s2, s21, 19
	s_lshl_b32 s21, s20, 5
	s_add_i32 s2, s2, s21
	s_add_i32 s2, s2, 0x34800000
	s_add_u32 s14, s92, s2
	s_addc_u32 s15, s93, 0
	s_branch .Lg3_wndw0
.Lg3_wsamew0:
	s_add_i32 s21, s11, 1
	s_lshl_b32 s2, s21, 19
	s_lshl_b32 s21, s20, 5
	s_add_i32 s2, s2, s21
	s_add_i32 s2, s2, 0x34800000
	s_add_u32 s14, s92, s2
	s_addc_u32 s15, s93, 0
.Lg3_wndw0:
.Lg3_swdw0:
	s_add_i32 s19, s19, 1
	s_add_i32 m0, s17, s20
	s_nop 0
	global_load_lds_dwordx4 v234, s[12:13]
	s_add_i32 m0, m0, 0x400
	s_nop 0
	global_load_lds_dwordx4 v235, s[12:13]
	s_add_i32 m0, m0, 0x400
	s_nop 0
	global_load_lds_dwordx4 v236, s[12:13]
	s_add_i32 m0, m0, 0x400
	s_nop 0
	global_load_lds_dwordx4 v237, s[12:13]
	s_cmp_eq_u32 s18, 13
	s_cbranch_scc1 .Lg3_saa1
	s_add_u32 s12, s12, 128
	s_addc_u32 s13, s13, 0
	s_branch .Lg3_sada1
.Lg3_saa1:
	s_cmp_lt_u32 s11, 3
	s_cbranch_scc1 .Lg3_samea1
	s_add_i32 s21, s10, s95
	s_cmpk_gt_i32 s21, 0x1ff
	s_cbranch_scc1 .Lg3_nda1
	s_lshl_b32 s2, s21, 18
	s_add_i32 s2, s2, 0x1e000000
	s_add_u32 s12, s92, s2
	s_addc_u32 s13, s93, 0
	s_branch .Lg3_nda1
.Lg3_samea1:
	s_lshl_b32 s2, s10, 18
	s_add_i32 s2, s2, 0x1e000000
	s_add_u32 s12, s92, s2
	s_addc_u32 s13, s93, 0
.Lg3_nda1:
.Lg3_sada1:
	v_add_u32_e32 v244, s16, v242
	v_add_u32_e32 v245, s16, v243
	ds_read_b128 v[198:201], v244 offset:0
	ds_read_b128 v[202:205], v244 offset:2048
	ds_read_b128 v[210:213], v244 offset:4096
	ds_read_b128 v[214:217], v244 offset:6144
	ds_read_b128 v[218:221], v244 offset:8192
	ds_read_b128 v[222:225], v244 offset:10240
	ds_read_b128 v[226:229], v244 offset:12288
	ds_read_b128 v[230:233], v244 offset:14336
	s_waitcnt lgkmcnt(4)
	v_mfma_f32_16x16x32_bf16 v[0:3], v[128:131], v[198:201], v[0:3]
	v_mfma_f32_16x16x32_bf16 v[32:35], v[132:135], v[198:201], v[32:35]
	v_mfma_f32_16x16x32_bf16 v[64:67], v[136:139], v[198:201], v[64:67]
	v_mfma_f32_16x16x32_bf16 v[96:99], v[140:143], v[198:201], v[96:99]
	v_mfma_f32_16x16x32_bf16 v[4:7], v[128:131], v[202:205], v[4:7]
	v_mfma_f32_16x16x32_bf16 v[36:39], v[132:135], v[202:205], v[36:39]
	v_mfma_f32_16x16x32_bf16 v[68:71], v[136:139], v[202:205], v[68:71]
	v_mfma_f32_16x16x32_bf16 v[100:103], v[140:143], v[202:205], v[100:103]
	v_mfma_f32_16x16x32_bf16 v[8:11], v[128:131], v[210:213], v[8:11]
	v_mfma_f32_16x16x32_bf16 v[40:43], v[132:135], v[210:213], v[40:43]
	v_mfma_f32_16x16x32_bf16 v[72:75], v[136:139], v[210:213], v[72:75]
	v_mfma_f32_16x16x32_bf16 v[104:107], v[140:143], v[210:213], v[104:107]
	v_mfma_f32_16x16x32_bf16 v[12:15], v[128:131], v[214:217], v[12:15]
	v_mfma_f32_16x16x32_bf16 v[44:47], v[132:135], v[214:217], v[44:47]
	v_mfma_f32_16x16x32_bf16 v[76:79], v[136:139], v[214:217], v[76:79]
	v_mfma_f32_16x16x32_bf16 v[108:111], v[140:143], v[214:217], v[108:111]
	s_waitcnt lgkmcnt(0)
	v_mfma_f32_16x16x32_bf16 v[16:19], v[128:131], v[218:221], v[16:19]
	v_mfma_f32_16x16x32_bf16 v[48:51], v[132:135], v[218:221], v[48:51]
	v_mfma_f32_16x16x32_bf16 v[80:83], v[136:139], v[218:221], v[80:83]
	v_mfma_f32_16x16x32_bf16 v[112:115], v[140:143], v[218:221], v[112:115]
	v_mfma_f32_16x16x32_bf16 v[20:23], v[128:131], v[222:225], v[20:23]
	v_mfma_f32_16x16x32_bf16 v[52:55], v[132:135], v[222:225], v[52:55]
	v_mfma_f32_16x16x32_bf16 v[84:87], v[136:139], v[222:225], v[84:87]
	v_mfma_f32_16x16x32_bf16 v[116:119], v[140:143], v[222:225], v[116:119]
	v_mfma_f32_16x16x32_bf16 v[24:27], v[128:131], v[226:229], v[24:27]
	v_mfma_f32_16x16x32_bf16 v[56:59], v[132:135], v[226:229], v[56:59]
	v_mfma_f32_16x16x32_bf16 v[88:91], v[136:139], v[226:229], v[88:91]
	v_mfma_f32_16x16x32_bf16 v[120:123], v[140:143], v[226:229], v[120:123]
	v_mfma_f32_16x16x32_bf16 v[28:31], v[128:131], v[230:233], v[28:31]
	v_mfma_f32_16x16x32_bf16 v[60:63], v[132:135], v[230:233], v[60:63]
	v_mfma_f32_16x16x32_bf16 v[92:95], v[136:139], v[230:233], v[92:95]
	v_mfma_f32_16x16x32_bf16 v[124:127], v[140:143], v[230:233], v[124:127]
	s_waitcnt vmcnt(16)
	global_load_dwordx4 v[128:131], v238, s[14:15]
	global_load_dwordx4 v[132:135], v239, s[14:15]
	global_load_dwordx4 v[136:139], v240, s[14:15]
	global_load_dwordx4 v[140:143], v241, s[14:15]
	s_cmp_eq_u32 s19, 31
	s_cbranch_scc1 .Lg3_sww2
	s_add_u32 s14, s14, 1024
	s_addc_u32 s15, s15, 0
	s_branch .Lg3_swdw2

.Lg3_wndw2:
.Lg3_swdw2:
	s_add_i32 s19, s19, 1
	ds_read_b128 v[198:201], v245 offset:0
	ds_read_b128 v[202:205], v245 offset:2048
	ds_read_b128 v[210:213], v245 offset:4096
	ds_read_b128 v[214:217], v245 offset:6144
	ds_read_b128 v[218:221], v245 offset:8192
	ds_read_b128 v[222:225], v245 offset:10240
	ds_read_b128 v[226:229], v245 offset:12288
	ds_read_b128 v[230:233], v245 offset:14336
	s_waitcnt lgkmcnt(4)
	v_mfma_f32_16x16x32_bf16 v[0:3], v[144:147], v[198:201], v[0:3]
	v_mfma_f32_16x16x32_bf16 v[32:35], v[148:151], v[198:201], v[32:35]
	v_mfma_f32_16x16x32_bf16 v[64:67], v[152:155], v[198:201], v[64:67]
	v_mfma_f32_16x16x32_bf16 v[96:99], v[156:159], v[198:201], v[96:99]
	v_mfma_f32_16x16x32_bf16 v[4:7], v[144:147], v[202:205], v[4:7]
	v_mfma_f32_16x16x32_bf16 v[36:39], v[148:151], v[202:205], v[36:39]
	v_mfma_f32_16x16x32_bf16 v[68:71], v[152:155], v[202:205], v[68:71]
	v_mfma_f32_16x16x32_bf16 v[100:103], v[156:159], v[202:205], v[100:103]
	v_mfma_f32_16x16x32_bf16 v[8:11], v[144:147], v[210:213], v[8:11]
	v_mfma_f32_16x16x32_bf16 v[40:43], v[148:151], v[210:213], v[40:43]
	v_mfma_f32_16x16x32_bf16 v[72:75], v[152:155], v[210:213], v[72:75]
	v_mfma_f32_16x16x32_bf16 v[104:107], v[156:159], v[210:213], v[104:107]
	v_mfma_f32_16x16x32_bf16 v[12:15], v[144:147], v[214:217], v[12:15]
	v_mfma_f32_16x16x32_bf16 v[44:47], v[148:151], v[214:217], v[44:47]
	v_mfma_f32_16x16x32_bf16 v[76:79], v[152:155], v[214:217], v[76:79]
	v_mfma_f32_16x16x32_bf16 v[108:111], v[156:159], v[214:217], v[108:111]
	s_waitcnt lgkmcnt(0)
	v_mfma_f32_16x16x32_bf16 v[16:19], v[144:147], v[218:221], v[16:19]
	v_mfma_f32_16x16x32_bf16 v[48:51], v[148:151], v[218:221], v[48:51]
	v_mfma_f32_16x16x32_bf16 v[80:83], v[152:155], v[218:221], v[80:83]
	v_mfma_f32_16x16x32_bf16 v[112:115], v[156:159], v[218:221], v[112:115]
	v_mfma_f32_16x16x32_bf16 v[20:23], v[144:147], v[222:225], v[20:23]
	v_mfma_f32_16x16x32_bf16 v[52:55], v[148:151], v[222:225], v[52:55]
	v_mfma_f32_16x16x32_bf16 v[84:87], v[152:155], v[222:225], v[84:87]
	v_mfma_f32_16x16x32_bf16 v[116:119], v[156:159], v[222:225], v[116:119]
	v_mfma_f32_16x16x32_bf16 v[24:27], v[144:147], v[226:229], v[24:27]
	v_mfma_f32_16x16x32_bf16 v[56:59], v[148:151], v[226:229], v[56:59]
	v_mfma_f32_16x16x32_bf16 v[88:91], v[152:155], v[226:229], v[88:91]
	v_mfma_f32_16x16x32_bf16 v[120:123], v[156:159], v[226:229], v[120:123]
	v_mfma_f32_16x16x32_bf16 v[28:31], v[144:147], v[230:233], v[28:31]
	v_mfma_f32_16x16x32_bf16 v[60:63], v[148:151], v[230:233], v[60:63]
	v_mfma_f32_16x16x32_bf16 v[92:95], v[152:155], v[230:233], v[92:95]
	v_mfma_f32_16x16x32_bf16 v[124:127], v[156:159], v[230:233], v[124:127]
	s_add_i32 s16, s16, 0x4000
	s_cmp_lt_u32 s16, 0xc000
	s_cselect_b32 s16, s16, 0
	s_add_i32 s17, s17, 0x4000
	s_cmp_lt_u32 s17, 0xc000
	s_cselect_b32 s17, s17, 0
	s_add_i32 s18, s18, 1
	s_waitcnt vmcnt(12)
	s_barrier
	global_load_dwordx4 v[144:147], v238, s[14:15]
	global_load_dwordx4 v[148:151], v239, s[14:15]
	global_load_dwordx4 v[152:155], v240, s[14:15]
	global_load_dwordx4 v[156:159], v241, s[14:15]
	s_cmp_eq_u32 s19, 31
	s_cbranch_scc1 .Lg3_sww3
	s_add_u32 s14, s14, 1024
	s_addc_u32 s15, s15, 0
	s_branch .Lg3_swdw3

.Lg3_nda4:
.Lg3_sada4:
	v_add_u32_e32 v244, s16, v242
	v_add_u32_e32 v245, s16, v243
	ds_read_b128 v[198:201], v244 offset:0
	ds_read_b128 v[202:205], v244 offset:2048
	ds_read_b128 v[210:213], v244 offset:4096
	ds_read_b128 v[214:217], v244 offset:6144
	ds_read_b128 v[218:221], v244 offset:8192
	ds_read_b128 v[222:225], v244 offset:10240
	ds_read_b128 v[226:229], v244 offset:12288
	ds_read_b128 v[230:233], v244 offset:14336
	s_waitcnt lgkmcnt(4)
	v_mfma_f32_16x16x32_bf16 v[0:3], v[160:163], v[198:201], v[0:3]
	v_mfma_f32_16x16x32_bf16 v[32:35], v[164:167], v[198:201], v[32:35]
	v_mfma_f32_16x16x32_bf16 v[64:67], v[168:171], v[198:201], v[64:67]
	v_mfma_f32_16x16x32_bf16 v[96:99], v[172:175], v[198:201], v[96:99]
	v_mfma_f32_16x16x32_bf16 v[4:7], v[160:163], v[202:205], v[4:7]
	v_mfma_f32_16x16x32_bf16 v[36:39], v[164:167], v[202:205], v[36:39]
	v_mfma_f32_16x16x32_bf16 v[68:71], v[168:171], v[202:205], v[68:71]
	v_mfma_f32_16x16x32_bf16 v[100:103], v[172:175], v[202:205], v[100:103]
	v_mfma_f32_16x16x32_bf16 v[8:11], v[160:163], v[210:213], v[8:11]
	v_mfma_f32_16x16x32_bf16 v[40:43], v[164:167], v[210:213], v[40:43]
	v_mfma_f32_16x16x32_bf16 v[72:75], v[168:171], v[210:213], v[72:75]
	v_mfma_f32_16x16x32_bf16 v[104:107], v[172:175], v[210:213], v[104:107]
	v_mfma_f32_16x16x32_bf16 v[12:15], v[160:163], v[214:217], v[12:15]
	v_mfma_f32_16x16x32_bf16 v[44:47], v[164:167], v[214:217], v[44:47]
	v_mfma_f32_16x16x32_bf16 v[76:79], v[168:171], v[214:217], v[76:79]
	v_mfma_f32_16x16x32_bf16 v[108:111], v[172:175], v[214:217], v[108:111]
	s_waitcnt lgkmcnt(0)
	v_mfma_f32_16x16x32_bf16 v[16:19], v[160:163], v[218:221], v[16:19]
	v_mfma_f32_16x16x32_bf16 v[48:51], v[164:167], v[218:221], v[48:51]
	v_mfma_f32_16x16x32_bf16 v[80:83], v[168:171], v[218:221], v[80:83]
	v_mfma_f32_16x16x32_bf16 v[112:115], v[172:175], v[218:221], v[112:115]
	v_mfma_f32_16x16x32_bf16 v[20:23], v[160:163], v[222:225], v[20:23]
	v_mfma_f32_16x16x32_bf16 v[52:55], v[164:167], v[222:225], v[52:55]
	v_mfma_f32_16x16x32_bf16 v[84:87], v[168:171], v[222:225], v[84:87]
	v_mfma_f32_16x16x32_bf16 v[116:119], v[172:175], v[222:225], v[116:119]
	v_mfma_f32_16x16x32_bf16 v[24:27], v[160:163], v[226:229], v[24:27]
	v_mfma_f32_16x16x32_bf16 v[56:59], v[164:167], v[226:229], v[56:59]
	v_mfma_f32_16x16x32_bf16 v[88:91], v[168:171], v[226:229], v[88:91]
	v_mfma_f32_16x16x32_bf16 v[120:123], v[172:175], v[226:229], v[120:123]
	v_mfma_f32_16x16x32_bf16 v[28:31], v[160:163], v[230:233], v[28:31]
	v_mfma_f32_16x16x32_bf16 v[60:63], v[164:167], v[230:233], v[60:63]
	v_mfma_f32_16x16x32_bf16 v[92:95], v[168:171], v[230:233], v[92:95]
	v_mfma_f32_16x16x32_bf16 v[124:127], v[172:175], v[230:233], v[124:127]
	s_waitcnt vmcnt(16)
	global_load_dwordx4 v[160:163], v238, s[14:15]
	global_load_dwordx4 v[164:167], v239, s[14:15]
	global_load_dwordx4 v[168:171], v240, s[14:15]
	global_load_dwordx4 v[172:175], v241, s[14:15]
	s_cmp_eq_u32 s19, 31
	s_cbranch_scc1 .Lg3_sww5
	s_add_u32 s14, s14, 1024
	s_addc_u32 s15, s15, 0
	s_branch .Lg3_swdw5

.Lg3_wndw5:
.Lg3_swdw5:
	s_add_i32 s19, s19, 1
	ds_read_b128 v[198:201], v245 offset:0
	ds_read_b128 v[202:205], v245 offset:2048
	ds_read_b128 v[210:213], v245 offset:4096
	ds_read_b128 v[214:217], v245 offset:6144
	ds_read_b128 v[218:221], v245 offset:8192
	ds_read_b128 v[222:225], v245 offset:10240
	ds_read_b128 v[226:229], v245 offset:12288
	ds_read_b128 v[230:233], v245 offset:14336
	s_waitcnt lgkmcnt(4)
	v_mfma_f32_16x16x32_bf16 v[0:3], v[176:179], v[198:201], v[0:3]
	v_mfma_f32_16x16x32_bf16 v[32:35], v[182:185], v[198:201], v[32:35]
	v_mfma_f32_16x16x32_bf16 v[64:67], v[186:189], v[198:201], v[64:67]
	v_mfma_f32_16x16x32_bf16 v[96:99], v[194:197], v[198:201], v[96:99]
	v_mfma_f32_16x16x32_bf16 v[4:7], v[176:179], v[202:205], v[4:7]
	v_mfma_f32_16x16x32_bf16 v[36:39], v[182:185], v[202:205], v[36:39]
	v_mfma_f32_16x16x32_bf16 v[68:71], v[186:189], v[202:205], v[68:71]
	v_mfma_f32_16x16x32_bf16 v[100:103], v[194:197], v[202:205], v[100:103]
	v_mfma_f32_16x16x32_bf16 v[8:11], v[176:179], v[210:213], v[8:11]
	v_mfma_f32_16x16x32_bf16 v[40:43], v[182:185], v[210:213], v[40:43]
	v_mfma_f32_16x16x32_bf16 v[72:75], v[186:189], v[210:213], v[72:75]
	v_mfma_f32_16x16x32_bf16 v[104:107], v[194:197], v[210:213], v[104:107]
	v_mfma_f32_16x16x32_bf16 v[12:15], v[176:179], v[214:217], v[12:15]
	v_mfma_f32_16x16x32_bf16 v[44:47], v[182:185], v[214:217], v[44:47]
	v_mfma_f32_16x16x32_bf16 v[76:79], v[186:189], v[214:217], v[76:79]
	v_mfma_f32_16x16x32_bf16 v[108:111], v[194:197], v[214:217], v[108:111]
	s_waitcnt lgkmcnt(0)
	v_mfma_f32_16x16x32_bf16 v[16:19], v[176:179], v[218:221], v[16:19]
	v_mfma_f32_16x16x32_bf16 v[48:51], v[182:185], v[218:221], v[48:51]
	v_mfma_f32_16x16x32_bf16 v[80:83], v[186:189], v[218:221], v[80:83]
	v_mfma_f32_16x16x32_bf16 v[112:115], v[194:197], v[218:221], v[112:115]
	v_mfma_f32_16x16x32_bf16 v[20:23], v[176:179], v[222:225], v[20:23]
	v_mfma_f32_16x16x32_bf16 v[52:55], v[182:185], v[222:225], v[52:55]
	v_mfma_f32_16x16x32_bf16 v[84:87], v[186:189], v[222:225], v[84:87]
	v_mfma_f32_16x16x32_bf16 v[116:119], v[194:197], v[222:225], v[116:119]
	v_mfma_f32_16x16x32_bf16 v[24:27], v[176:179], v[226:229], v[24:27]
	v_mfma_f32_16x16x32_bf16 v[56:59], v[182:185], v[226:229], v[56:59]
	v_mfma_f32_16x16x32_bf16 v[88:91], v[186:189], v[226:229], v[88:91]
	v_mfma_f32_16x16x32_bf16 v[120:123], v[194:197], v[226:229], v[120:123]
	v_mfma_f32_16x16x32_bf16 v[28:31], v[176:179], v[230:233], v[28:31]
	v_mfma_f32_16x16x32_bf16 v[60:63], v[182:185], v[230:233], v[60:63]
	v_mfma_f32_16x16x32_bf16 v[92:95], v[186:189], v[230:233], v[92:95]
	v_mfma_f32_16x16x32_bf16 v[124:127], v[194:197], v[230:233], v[124:127]
	s_add_i32 s16, s16, 0x4000
	s_cmp_lt_u32 s16, 0xc000
	s_cselect_b32 s16, s16, 0
	s_add_i32 s17, s17, 0x4000
	s_cmp_lt_u32 s17, 0xc000
	s_cselect_b32 s17, s17, 0
	s_add_i32 s18, s18, 1
	s_cmp_lt_u32 s18, 16
	s_cbranch_scc1 .Lg3_loop
	s_nop 7
	s_nop 7
	v_and_b32_e32 v198, 63, v208
	v_lshrrev_b32_e32 v199, 6, v208
	v_and_b32_e32 v200, 15, v198
	v_lshrrev_b32_e32 v201, 4, v198
	s_lshl_b32 s2, s10, 18
	s_lshl_b32 s21, s11, 9
	s_add_i32 s2, s2, s21
	s_add_i32 s2, s2, 0x26000000
	v_lshlrev_b32_e32 v244, 11, v200
	v_lshl_add_u32 v244, v199, 7, v244
	v_lshl_add_u32 v244, v201, 3, v244
	v_add_u32_e32 v244, s2, v244
	v_mov_b32_e32 v245, s93
	v_add_co_u32_e32 v244, vcc, s92, v244
	s_nop 1
	v_addc_co_u32_e32 v245, vcc, 0, v245, vcc
	v_mul_f32_e32 v0, v246, v0
	v_mul_f32_e32 v1, v246, v1
	v_mul_f32_e32 v2, v246, v2
	v_mul_f32_e32 v3, v246, v3
	v_cvt_pk_bf16_f32 v202, v0, v1
	v_cvt_pk_bf16_f32 v203, v2, v3
	global_store_dwordx2 v[244:245], v[202:203], off offset:0
	v_mul_f32_e32 v32, v246, v32
	v_mul_f32_e32 v33, v246, v33
	v_mul_f32_e32 v34, v246, v34
	v_mul_f32_e32 v35, v246, v35
	v_cvt_pk_bf16_f32 v204, v32, v33
	v_cvt_pk_bf16_f32 v205, v34, v35
	global_store_dwordx2 v[244:245], v[204:205], off offset:32
	v_mul_f32_e32 v64, v246, v64
	v_mul_f32_e32 v65, v246, v65
	v_mul_f32_e32 v66, v246, v66
	v_mul_f32_e32 v67, v246, v67
	v_cvt_pk_bf16_f32 v210, v64, v65
	v_cvt_pk_bf16_f32 v211, v66, v67
	global_store_dwordx2 v[244:245], v[210:211], off offset:64
	v_mul_f32_e32 v96, v246, v96
	v_mul_f32_e32 v97, v246, v97
	v_mul_f32_e32 v98, v246, v98
	v_mul_f32_e32 v99, v246, v99
	v_cvt_pk_bf16_f32 v212, v96, v97
	v_cvt_pk_bf16_f32 v213, v98, v99
	global_store_dwordx2 v[244:245], v[212:213], off offset:96
	v_add_co_u32_e32 v244, vcc, 0x8000, v244
	s_nop 1
	v_addc_co_u32_e32 v245, vcc, 0, v245, vcc
	v_mul_f32_e32 v4, v247, v4
	v_mul_f32_e32 v5, v247, v5
	v_mul_f32_e32 v6, v247, v6
	v_mul_f32_e32 v7, v247, v7
	v_cvt_pk_bf16_f32 v202, v4, v5
	v_cvt_pk_bf16_f32 v203, v6, v7
	global_store_dwordx2 v[244:245], v[202:203], off offset:0
	v_mul_f32_e32 v36, v247, v36
	v_mul_f32_e32 v37, v247, v37
	v_mul_f32_e32 v38, v247, v38
	v_mul_f32_e32 v39, v247, v39
	v_cvt_pk_bf16_f32 v204, v36, v37
	v_cvt_pk_bf16_f32 v205, v38, v39
	global_store_dwordx2 v[244:245], v[204:205], off offset:32
	v_mul_f32_e32 v68, v247, v68
	v_mul_f32_e32 v69, v247, v69
	v_mul_f32_e32 v70, v247, v70
	v_mul_f32_e32 v71, v247, v71
	v_cvt_pk_bf16_f32 v210, v68, v69
	v_cvt_pk_bf16_f32 v211, v70, v71
	global_store_dwordx2 v[244:245], v[210:211], off offset:64
	v_mul_f32_e32 v100, v247, v100
	v_mul_f32_e32 v101, v247, v101
	v_mul_f32_e32 v102, v247, v102
	v_mul_f32_e32 v103, v247, v103
	v_cvt_pk_bf16_f32 v212, v100, v101
	v_cvt_pk_bf16_f32 v213, v102, v103
	global_store_dwordx2 v[244:245], v[212:213], off offset:96
	v_add_co_u32_e32 v244, vcc, 0x8000, v244
	s_nop 1
	v_addc_co_u32_e32 v245, vcc, 0, v245, vcc
	v_mul_f32_e32 v8, v248, v8
	v_mul_f32_e32 v9, v248, v9
	v_mul_f32_e32 v10, v248, v10
	v_mul_f32_e32 v11, v248, v11
	v_cvt_pk_bf16_f32 v202, v8, v9
	v_cvt_pk_bf16_f32 v203, v10, v11
	global_store_dwordx2 v[244:245], v[202:203], off offset:0
	v_mul_f32_e32 v40, v248, v40
	v_mul_f32_e32 v41, v248, v41
	v_mul_f32_e32 v42, v248, v42
	v_mul_f32_e32 v43, v248, v43
	v_cvt_pk_bf16_f32 v204, v40, v41
	v_cvt_pk_bf16_f32 v205, v42, v43
	global_store_dwordx2 v[244:245], v[204:205], off offset:32
	v_mul_f32_e32 v72, v248, v72
	v_mul_f32_e32 v73, v248, v73
	v_mul_f32_e32 v74, v248, v74
	v_mul_f32_e32 v75, v248, v75
	v_cvt_pk_bf16_f32 v210, v72, v73
	v_cvt_pk_bf16_f32 v211, v74, v75
	global_store_dwordx2 v[244:245], v[210:211], off offset:64
	v_mul_f32_e32 v104, v248, v104
	v_mul_f32_e32 v105, v248, v105
	v_mul_f32_e32 v106, v248, v106
	v_mul_f32_e32 v107, v248, v107
	v_cvt_pk_bf16_f32 v212, v104, v105
	v_cvt_pk_bf16_f32 v213, v106, v107
	global_store_dwordx2 v[244:245], v[212:213], off offset:96
	v_add_co_u32_e32 v244, vcc, 0x8000, v244
	s_nop 1
	v_addc_co_u32_e32 v245, vcc, 0, v245, vcc
	v_mul_f32_e32 v12, v249, v12
	v_mul_f32_e32 v13, v249, v13
	v_mul_f32_e32 v14, v249, v14
	v_mul_f32_e32 v15, v249, v15
	v_cvt_pk_bf16_f32 v202, v12, v13
	v_cvt_pk_bf16_f32 v203, v14, v15
	global_store_dwordx2 v[244:245], v[202:203], off offset:0
	v_mul_f32_e32 v44, v249, v44
	v_mul_f32_e32 v45, v249, v45
	v_mul_f32_e32 v46, v249, v46
	v_mul_f32_e32 v47, v249, v47
	v_cvt_pk_bf16_f32 v204, v44, v45
	v_cvt_pk_bf16_f32 v205, v46, v47
	global_store_dwordx2 v[244:245], v[204:205], off offset:32
	v_mul_f32_e32 v76, v249, v76
	v_mul_f32_e32 v77, v249, v77
	v_mul_f32_e32 v78, v249, v78
	v_mul_f32_e32 v79, v249, v79
	v_cvt_pk_bf16_f32 v210, v76, v77
	v_cvt_pk_bf16_f32 v211, v78, v79
	global_store_dwordx2 v[244:245], v[210:211], off offset:64
	v_mul_f32_e32 v108, v249, v108
	v_mul_f32_e32 v109, v249, v109
	v_mul_f32_e32 v110, v249, v110
	v_mul_f32_e32 v111, v249, v111
	v_cvt_pk_bf16_f32 v212, v108, v109
	v_cvt_pk_bf16_f32 v213, v110, v111
	global_store_dwordx2 v[244:245], v[212:213], off offset:96
	v_add_co_u32_e32 v244, vcc, 0x8000, v244
	s_nop 1
	v_addc_co_u32_e32 v245, vcc, 0, v245, vcc
	v_mul_f32_e32 v16, v250, v16
	v_mul_f32_e32 v17, v250, v17
	v_mul_f32_e32 v18, v250, v18
	v_mul_f32_e32 v19, v250, v19
	v_cvt_pk_bf16_f32 v202, v16, v17
	v_cvt_pk_bf16_f32 v203, v18, v19
	global_store_dwordx2 v[244:245], v[202:203], off offset:0
	v_mul_f32_e32 v48, v250, v48
	v_mul_f32_e32 v49, v250, v49
	v_mul_f32_e32 v50, v250, v50
	v_mul_f32_e32 v51, v250, v51
	v_cvt_pk_bf16_f32 v204, v48, v49
	v_cvt_pk_bf16_f32 v205, v50, v51
	global_store_dwordx2 v[244:245], v[204:205], off offset:32
	v_mul_f32_e32 v80, v250, v80
	v_mul_f32_e32 v81, v250, v81
	v_mul_f32_e32 v82, v250, v82
	v_mul_f32_e32 v83, v250, v83
	v_cvt_pk_bf16_f32 v210, v80, v81
	v_cvt_pk_bf16_f32 v211, v82, v83
	global_store_dwordx2 v[244:245], v[210:211], off offset:64
	v_mul_f32_e32 v112, v250, v112
	v_mul_f32_e32 v113, v250, v113
	v_mul_f32_e32 v114, v250, v114
	v_mul_f32_e32 v115, v250, v115
	v_cvt_pk_bf16_f32 v212, v112, v113
	v_cvt_pk_bf16_f32 v213, v114, v115
	global_store_dwordx2 v[244:245], v[212:213], off offset:96
	v_add_co_u32_e32 v244, vcc, 0x8000, v244
	s_nop 1
	v_addc_co_u32_e32 v245, vcc, 0, v245, vcc
	v_mul_f32_e32 v20, v251, v20
	v_mul_f32_e32 v21, v251, v21
	v_mul_f32_e32 v22, v251, v22
	v_mul_f32_e32 v23, v251, v23
	v_cvt_pk_bf16_f32 v202, v20, v21
	v_cvt_pk_bf16_f32 v203, v22, v23
	global_store_dwordx2 v[244:245], v[202:203], off offset:0
	v_mul_f32_e32 v52, v251, v52
	v_mul_f32_e32 v53, v251, v53
	v_mul_f32_e32 v54, v251, v54
	v_mul_f32_e32 v55, v251, v55
	v_cvt_pk_bf16_f32 v204, v52, v53
	v_cvt_pk_bf16_f32 v205, v54, v55
	global_store_dwordx2 v[244:245], v[204:205], off offset:32
	v_mul_f32_e32 v84, v251, v84
	v_mul_f32_e32 v85, v251, v85
	v_mul_f32_e32 v86, v251, v86
	v_mul_f32_e32 v87, v251, v87
	v_cvt_pk_bf16_f32 v210, v84, v85
	v_cvt_pk_bf16_f32 v211, v86, v87
	global_store_dwordx2 v[244:245], v[210:211], off offset:64
	v_mul_f32_e32 v116, v251, v116
	v_mul_f32_e32 v117, v251, v117
	v_mul_f32_e32 v118, v251, v118
	v_mul_f32_e32 v119, v251, v119
	v_cvt_pk_bf16_f32 v212, v116, v117
	v_cvt_pk_bf16_f32 v213, v118, v119
	global_store_dwordx2 v[244:245], v[212:213], off offset:96
	v_add_co_u32_e32 v244, vcc, 0x8000, v244
	s_nop 1
	v_addc_co_u32_e32 v245, vcc, 0, v245, vcc
	v_mul_f32_e32 v24, v252, v24
	v_mul_f32_e32 v25, v252, v25
	v_mul_f32_e32 v26, v252, v26
	v_mul_f32_e32 v27, v252, v27
	v_cvt_pk_bf16_f32 v202, v24, v25
	v_cvt_pk_bf16_f32 v203, v26, v27
	global_store_dwordx2 v[244:245], v[202:203], off offset:0
	v_mul_f32_e32 v56, v252, v56
	v_mul_f32_e32 v57, v252, v57
	v_mul_f32_e32 v58, v252, v58
	v_mul_f32_e32 v59, v252, v59
	v_cvt_pk_bf16_f32 v204, v56, v57
	v_cvt_pk_bf16_f32 v205, v58, v59
	global_store_dwordx2 v[244:245], v[204:205], off offset:32
	v_mul_f32_e32 v88, v252, v88
	v_mul_f32_e32 v89, v252, v89
	v_mul_f32_e32 v90, v252, v90
	v_mul_f32_e32 v91, v252, v91
	v_cvt_pk_bf16_f32 v210, v88, v89
	v_cvt_pk_bf16_f32 v211, v90, v91
	global_store_dwordx2 v[244:245], v[210:211], off offset:64
	v_mul_f32_e32 v120, v252, v120
	v_mul_f32_e32 v121, v252, v121
	v_mul_f32_e32 v122, v252, v122
	v_mul_f32_e32 v123, v252, v123
	v_cvt_pk_bf16_f32 v212, v120, v121
	v_cvt_pk_bf16_f32 v213, v122, v123
	global_store_dwordx2 v[244:245], v[212:213], off offset:96
	v_add_co_u32_e32 v244, vcc, 0x8000, v244
	s_nop 1
	v_addc_co_u32_e32 v245, vcc, 0, v245, vcc
	v_mul_f32_e32 v28, v253, v28
	v_mul_f32_e32 v29, v253, v29
	v_mul_f32_e32 v30, v253, v30
	v_mul_f32_e32 v31, v253, v31
	v_cvt_pk_bf16_f32 v202, v28, v29
	v_cvt_pk_bf16_f32 v203, v30, v31
	global_store_dwordx2 v[244:245], v[202:203], off offset:0
	v_mul_f32_e32 v60, v253, v60
	v_mul_f32_e32 v61, v253, v61
	v_mul_f32_e32 v62, v253, v62
	v_mul_f32_e32 v63, v253, v63
	v_cvt_pk_bf16_f32 v204, v60, v61
	v_cvt_pk_bf16_f32 v205, v62, v63
	global_store_dwordx2 v[244:245], v[204:205], off offset:32
	v_mul_f32_e32 v92, v253, v92
	v_mul_f32_e32 v93, v253, v93
	v_mul_f32_e32 v94, v253, v94
	v_mul_f32_e32 v95, v253, v95
	v_cvt_pk_bf16_f32 v210, v92, v93
	v_cvt_pk_bf16_f32 v211, v94, v95
	global_store_dwordx2 v[244:245], v[210:211], off offset:64
	v_mul_f32_e32 v124, v253, v124
	v_mul_f32_e32 v125, v253, v125
	v_mul_f32_e32 v126, v253, v126
	v_mul_f32_e32 v127, v253, v127
	v_cvt_pk_bf16_f32 v212, v124, v125
	v_cvt_pk_bf16_f32 v213, v126, v127
	global_store_dwordx2 v[244:245], v[212:213], off offset:96
	s_add_i32 s11, s11, 1
	s_cmp_lt_u32 s11, 4
	s_cbranch_scc1 .Lg3_chunk
	s_mov_b32 s11, 0
	s_add_i32 s10, s10, s95
	s_cmpk_gt_i32 s10, 0x1ff
	s_cbranch_scc1 .Lg3_done
	v_and_b32_e32 v244, 15, v208
	v_lshlrev_b32_e32 v244, 2, v244
	s_lshl_b32 s2, s10, 9
	s_add_i32 s2, s2, 0x36c80000
	v_add_u32_e32 v244, s2, v244
	v_mov_b32_e32 v245, s93
	v_add_co_u32_e32 v244, vcc, s92, v244
	s_nop 1
	v_addc_co_u32_e32 v245, vcc, 0, v245, vcc
	global_load_dword v246, v[244:245], off
	global_load_dword v247, v[244:245], off offset:64
	global_load_dword v248, v[244:245], off offset:128
	global_load_dword v249, v[244:245], off offset:192
	global_load_dword v250, v[244:245], off offset:256
	global_load_dword v251, v[244:245], off offset:320
	global_load_dword v252, v[244:245], off offset:384
	global_load_dword v253, v[244:245], off offset:448
	s_branch .Lg3_chunk
.Lg3_done:
	s_waitcnt vmcnt(0)

